# previous best plus one more spacing nop after a VALU carry-out before the scalar register is reused
# baseline (speedup 1.0000x reference)
.LBB0_658:
	s_mov_b64 s[4:5], s[0:1]
	s_load_dwordx2 s[8:9], s[4:5], 0xd8
	s_and_b32 s4, s2, 0xff
	s_lshl_b32 s5, s2, 5
	s_and_b32 s5, s5, 0x4000
	s_lshl_b32 s6, s4, 6
	s_or_b32 s5, s6, s5
	s_mulk_i32 s5, 0x1800
	s_waitcnt lgkmcnt(0)
	s_add_u32 s5, s8, s5
	s_addc_u32 s6, s9, 0
	s_add_u32 s5, s5, 0x9800000
	s_addc_u32 s10, s6, 0
	s_cmpk_lt_u32 s2, 0x400
	s_cselect_b64 s[6:7], -1, 0
	s_and_b64 vcc, s[6:7], exec
	s_movk_i32 s6, 0x600
	s_cselect_b32 s11, s6, 0x800
	s_movk_i32 s6, 0x700
	s_cselect_b32 s6, s6, 0x900
	s_add_u32 s6, s5, s6
	s_addc_u32 s7, s10, 0
	s_lshr_b32 s12, s2, 1
	s_and_b32 s12, s12, 0x80
	s_add_u32 s6, s6, s12
	s_addc_u32 s7, s7, 0
	v_lshl_add_u64 v[28:29], s[6:7], 0, v[10:11]
	v_mov_b32_e32 v13, v11
	v_lshl_add_u64 v[30:31], v[28:29], 0, v[12:13]
	global_load_dwordx4 v[44:47], v[30:31], off
	v_mov_b32_e32 v15, v11
	v_mov_b32_e32 v17, v11
	v_mov_b32_e32 v19, v11
	v_mov_b32_e32 v21, v11
	v_mov_b32_e32 v23, v11
	v_mov_b32_e32 v25, v11
	s_add_u32 s5, s5, s11
	s_mov_b32 s6, 0xc000
	v_add_co_u32_e64 v80, s[6:7], s6, v30
	s_nop 1
	v_addc_co_u32_e64 v81, s[6:7], 0, v31, s[6:7]
	global_load_dwordx4 v[48:51], v[80:81], off
	s_mov_b32 s6, 0x18000
	v_add_co_u32_e64 v82, s[6:7], s6, v30
	s_nop 1
	v_addc_co_u32_e64 v83, s[6:7], 0, v31, s[6:7]
	global_load_dwordx4 v[52:55], v[82:83], off
	s_mov_b32 s6, 0x24000
	v_add_co_u32_e64 v84, s[6:7], s6, v30
	s_nop 1
	v_addc_co_u32_e64 v85, s[6:7], 0, v31, s[6:7]
	global_load_dwordx4 v[56:59], v[84:85], off
	s_addc_u32 s7, s10, 0
	s_add_u32 s6, s5, s12
	s_addc_u32 s7, s7, 0
	s_lshl_b32 s10, s4, 12
	v_lshl_add_u64 v[86:87], v[28:29], 0, v[14:15]
	global_load_dwordx4 v[60:63], v[86:87], off
	v_lshl_add_u64 v[88:89], v[28:29], 0, v[16:17]
	global_load_dwordx4 v[64:67], v[88:89], off
	v_lshl_add_u64 v[90:91], v[28:29], 0, v[18:19]
	global_load_dwordx4 v[68:71], v[90:91], off
	v_lshl_add_u64 v[92:93], v[28:29], 0, v[20:21]
	global_load_dwordx4 v[72:75], v[92:93], off
	v_lshl_add_u64 v[28:29], s[6:7], 0, v[22:23]
	v_lshl_add_u64 v[30:31], v[28:29], 0, v[24:25]
	s_mov_b32 s6, 0x18000
	v_add_co_u32_e64 v94, s[6:7], s6, v30
	s_nop 1
	v_addc_co_u32_e64 v95, s[6:7], 0, v31, s[6:7]
	s_nop 1
	s_mov_b32 s6, 0x30000
	v_add_co_u32_e64 v96, s[6:7], s6, v30
	s_nop 1
	v_addc_co_u32_e64 v97, s[6:7], 0, v31, s[6:7]
	v_lshlrev_b32_e32 v98, 1, v6
	v_mov_b32_e32 v99, v11
	v_lshl_add_u64 v[98:99], v[28:29], 0, v[98:99]
	global_load_dwordx4 v[104:107], v[30:31], off
	global_load_dwordx4 v[108:111], v[30:31], off offset:64
	global_load_dwordx4 v[112:115], v[94:95], off
	global_load_dwordx4 v[116:119], v[94:95], off offset:64
	global_load_dwordx4 v[120:123], v[96:97], off
	global_load_dwordx4 v[124:127], v[96:97], off offset:64
	global_load_dwordx4 v[128:131], v[98:99], off
	global_load_dwordx4 v[132:135], v[98:99], off offset:64
	s_mov_b64 s[6:7], -1
	s_waitcnt vmcnt(15)
	ds_write2_b32 v35, v44, v45 offset1:1
	ds_write2_b32 v35, v46, v47 offset0:2 offset1:3
	s_waitcnt vmcnt(14)
	v_add_u32_e32 v100, 0x420, v35
	v_add_u32_e32 v101, 0x428, v35
	ds_write2_b32 v100, v48, v49 offset1:1
	ds_write2_b32 v101, v50, v51 offset1:1
	s_waitcnt vmcnt(13)
	v_add_u32_e32 v100, 0x840, v35
	v_add_u32_e32 v101, 0x848, v35
	ds_write2_b32 v100, v52, v53 offset1:1
	ds_write2_b32 v101, v54, v55 offset1:1
	s_waitcnt vmcnt(12)
	v_add_u32_e32 v100, 0xc60, v35
	v_add_u32_e32 v101, 0xc68, v35
	ds_write2_b32 v100, v56, v57 offset1:1
	ds_write2_b32 v101, v58, v59 offset1:1
	s_waitcnt vmcnt(11)
	v_add_u32_e32 v100, 0x1080, v35
	v_add_u32_e32 v101, 0x1088, v35
	ds_write2_b32 v100, v60, v61 offset1:1
	ds_write2_b32 v101, v62, v63 offset1:1
	s_waitcnt vmcnt(10)
	v_add_u32_e32 v100, 0x14a0, v35
	v_add_u32_e32 v101, 0x14a8, v35
	ds_write2_b32 v100, v64, v65 offset1:1
	ds_write2_b32 v101, v66, v67 offset1:1
	s_waitcnt vmcnt(9)
	v_add_u32_e32 v100, 0x18c0, v35
	v_add_u32_e32 v101, 0x18c8, v35
	ds_write2_b32 v100, v68, v69 offset1:1
	ds_write2_b32 v101, v70, v71 offset1:1
	s_waitcnt vmcnt(8)
	v_add_u32_e32 v100, 0x1ce0, v35
	v_add_u32_e32 v101, 0x1ce8, v35
	ds_write2_b32 v100, v72, v73 offset1:1
	ds_write2_b32 v101, v74, v75 offset1:1
	v_add_u32_e32 v13, 0x1ce0, v35
	s_cbranch_vccnz .LBB0_660
	s_waitcnt vmcnt(0)
	s_bfe_u32 s4, s2, 0x20008
	s_lshl_b32 s4, s4, 21
	s_lshl_b32 s5, s10, 1
	s_add_u32 s4, s8, s4
	s_addc_u32 s6, s9, 0
	s_add_u32 s4, s4, s5
	s_addc_u32 s5, s6, 0
	s_add_u32 s6, s4, 0x19100000
	s_addc_u32 s7, s5, 0
	s_mov_b32 s11, 0x18000
	v_add_co_u32_e32 v38, vcc, s11, v30
	s_mov_b32 s11, 0x30000
	s_nop 0
	v_addc_co_u32_e32 v39, vcc, 0, v31, vcc
	v_mov_b32_e32 v27, v11
	v_lshl_add_u64 v[32:33], s[6:7], 0, v[26:27]
	s_nop 0
	global_store_dwordx4 v26, v[104:107], s[6:7]
	s_nop 0
	s_nop 0
	global_store_dwordx4 v26, v[108:111], s[6:7] offset:1024
	s_nop 0
	s_nop 0
	global_store_dwordx4 v26, v[112:115], s[6:7] offset:2048
	s_nop 0
	v_add_co_u32_e32 v38, vcc, s11, v30
	s_movk_i32 s11, 0x1000
	s_nop 0
	v_addc_co_u32_e32 v39, vcc, 0, v31, vcc
	v_add_co_u32_e32 v32, vcc, s11, v32
	s_nop 0
	global_store_dwordx4 v26, v[116:119], s[6:7] offset:3072
	s_nop 0
	v_addc_co_u32_e32 v33, vcc, 0, v33, vcc
	s_nop 0
	global_store_dwordx4 v36, v[120:123], s[6:7]
	s_nop 0
	s_nop 0
	global_store_dwordx4 v37, v[124:127], s[6:7]
	s_nop 1
	v_lshlrev_b32_e32 v2, 1, v6
	v_mov_b32_e32 v3, v11
	v_lshl_add_u64 v[38:39], v[28:29], 0, v[2:3]
	s_nop 0
	s_add_u32 s6, s4, 0x18100000
	s_addc_u32 s7, s5, 0
	s_nop 0
	global_store_dwordx4 v[32:33], v[128:131], off offset:2048
	s_nop 0
	s_nop 0
	global_store_dwordx4 v[32:33], v[132:135], off offset:3072
	s_waitcnt lgkmcnt(0)
	ds_read_u16 v2, v7 offset:2112
	ds_read_u16 v13, v7 offset:132
	ds_read_u16 v3, v7 offset:2244
	ds_read_u16 v15, v7 offset:264
	ds_read_u16 v4, v7 offset:2376
	ds_read_u16 v17, v7 offset:396
	ds_read_u16 v5, v7 offset:2508
	v_lshl_add_u64 v[32:33], s[6:7], 0, v[26:27]
	v_add_co_u32_e32 v32, vcc, s11, v32
	s_waitcnt lgkmcnt(0)
	v_perm_b32 v5, v5, v4, s43
	v_perm_b32 v4, v3, v2, s43
	v_perm_b32 v3, v17, v15, s43
	ds_read_u16 v2, v7
	ds_read_u16 v15, v7 offset:32
	v_addc_co_u32_e32 v33, vcc, 0, v33, vcc
	s_waitcnt lgkmcnt(1)
	v_perm_b32 v2, v13, v2, s43
	global_store_dwordx4 v26, v[2:5], s[6:7]
	ds_read_u16 v2, v7 offset:2144
	ds_read_u16 v13, v7 offset:164
	ds_read_u16 v3, v7 offset:2276
	ds_read_u16 v17, v7 offset:296
	ds_read_u16 v4, v7 offset:2408
	ds_read_u16 v19, v7 offset:428
	ds_read_u16 v5, v7 offset:2540
	s_waitcnt lgkmcnt(0)
	v_perm_b32 v5, v5, v4, s43
	v_perm_b32 v4, v3, v2, s43
	v_perm_b32 v3, v19, v17, s43
	v_perm_b32 v2, v13, v15, s43
	global_store_dwordx4 v26, v[2:5], s[6:7] offset:1024
	ds_read_u16 v2, v7 offset:2176
	ds_read_u16 v13, v7 offset:196
	ds_read_u16 v3, v7 offset:2308
	ds_read_u16 v15, v7 offset:328
	ds_read_u16 v4, v7 offset:2440
	ds_read_u16 v17, v7 offset:460
	ds_read_u16 v5, v7 offset:2572
	s_waitcnt lgkmcnt(0)
	v_perm_b32 v5, v5, v4, s43
	v_perm_b32 v4, v3, v2, s43
	v_perm_b32 v3, v17, v15, s43
	ds_read_u16 v2, v7 offset:64
	ds_read_u16 v15, v7 offset:96
	s_waitcnt lgkmcnt(1)
	v_perm_b32 v2, v13, v2, s43
	global_store_dwordx4 v26, v[2:5], s[6:7] offset:2048
	ds_read_u16 v2, v7 offset:2208
	ds_read_u16 v13, v7 offset:228
	ds_read_u16 v3, v7 offset:2340
	ds_read_u16 v17, v7 offset:360
	ds_read_u16 v4, v7 offset:2472
	ds_read_u16 v19, v7 offset:492
	ds_read_u16 v5, v7 offset:2604
	s_waitcnt lgkmcnt(0)
	v_perm_b32 v5, v5, v4, s43
	v_perm_b32 v4, v3, v2, s43
	v_perm_b32 v3, v19, v17, s43
	v_perm_b32 v2, v13, v15, s43
	global_store_dwordx4 v26, v[2:5], s[6:7] offset:3072
	ds_read_u16 v2, v7 offset:4224
	ds_read_u16 v3, v7 offset:6336
	ds_read_u16 v13, v7 offset:4356
	ds_read_u16 v4, v7 offset:6468
	ds_read_u16 v15, v7 offset:4488
	ds_read_u16 v5, v7 offset:6600
	ds_read_u16 v17, v7 offset:4620
	ds_read_u16 v19, v7 offset:6732
	s_waitcnt lgkmcnt(4)
	v_perm_b32 v4, v4, v3, s43
	v_perm_b32 v2, v13, v2, s43
	s_waitcnt lgkmcnt(1)
	v_perm_b32 v3, v17, v15, s43
	s_waitcnt lgkmcnt(0)
	v_perm_b32 v5, v19, v5, s43
	global_store_dwordx4 v36, v[2:5], s[6:7]
	ds_read_u16 v2, v7 offset:4256
	ds_read_u16 v3, v7 offset:6368
	ds_read_u16 v13, v7 offset:4388
	ds_read_u16 v4, v7 offset:6500
	ds_read_u16 v15, v7 offset:4520
	ds_read_u16 v5, v7 offset:6632
	ds_read_u16 v17, v7 offset:4652
	ds_read_u16 v19, v7 offset:6764
	s_waitcnt lgkmcnt(4)
	v_perm_b32 v4, v4, v3, s43
	v_perm_b32 v2, v13, v2, s43
	s_waitcnt lgkmcnt(1)
	v_perm_b32 v3, v17, v15, s43
	s_waitcnt lgkmcnt(0)
	v_perm_b32 v5, v19, v5, s43
	global_store_dwordx4 v37, v[2:5], s[6:7]
	ds_read_u16 v2, v7 offset:4288
	ds_read_u16 v3, v7 offset:6400
	ds_read_u16 v13, v7 offset:4420
	ds_read_u16 v4, v7 offset:6532
	ds_read_u16 v15, v7 offset:4552
	ds_read_u16 v5, v7 offset:6664
	ds_read_u16 v17, v7 offset:4684
	ds_read_u16 v19, v7 offset:6796
	s_waitcnt lgkmcnt(4)
	v_perm_b32 v4, v4, v3, s43
	v_perm_b32 v2, v13, v2, s43
	s_mov_b64 s[6:7], 0
	s_waitcnt lgkmcnt(1)
	v_perm_b32 v3, v17, v15, s43
	s_waitcnt lgkmcnt(0)
	v_perm_b32 v5, v19, v5, s43
	global_store_dwordx4 v[32:33], v[2:5], off offset:2048
	ds_read_u16 v2, v7 offset:4320
	ds_read_u16 v3, v7 offset:6432
	ds_read_u16 v13, v7 offset:4452
	ds_read_u16 v4, v7 offset:6564
	ds_read_u16 v15, v7 offset:4584
	ds_read_u16 v5, v7 offset:6696
	ds_read_u16 v17, v7 offset:4716
	ds_read_u16 v19, v7 offset:6828
	s_waitcnt lgkmcnt(4)
	v_perm_b32 v4, v4, v3, s43
	v_perm_b32 v2, v13, v2, s43
	s_waitcnt lgkmcnt(1)
	v_perm_b32 v3, v17, v15, s43
	s_waitcnt lgkmcnt(0)
	v_perm_b32 v5, v19, v5, s43
	global_store_dwordx4 v[32:33], v[2:5], off offset:3072
